# GEMM main loops: LDS-DMA completion waits moved to every load segment as vmcnt(10) (each stage gets 5 phases to land instead of 3 with hipcc's two vmcnt(6))
# speedup vs baseline: 1.0023x; 1.0023x over previous
; #define PG8_STAGE(bufoff, gbase, voff) do { _Pragma("unroll") for (int _i = 0; _i < 2; ++_i) \
;         __builtin_amdgcn_global_load_lds((const unsigned*)((const char*)(gbase) + (voff)[_i]), (LAS unsigned*)(lds + (bufoff) + ldsw + _i * 8192), 16, 0, 0); } while (0)
; #define PG8_LDA(dst, b, h) do { _Pragma("unroll") for (int m = 0; m < 4; ++m) _Pragma("unroll") for (int k = 0; k < 2; ++k) dst[m][k] = *(const LAS bf16x8*)(lds + PG8_SA(b, h) + aoff + m * 2048 + k * 1024); } while (0)
; #define PG8_LDB(dst, b, h) do { _Pragma("unroll") for (int n = 0; n < 2; ++n) _Pragma("unroll") for (int k = 0; k < 2; ++k) dst[n][k] = *(const LAS bf16x8*)(lds + PG8_SB(b, h) + boff + n * 2048 + k * 1024); } while (0)
; #define PG8_MMA(ai, bj, At, Bt) do { __builtin_amdgcn_s_setprio(1); _Pragma("unroll") for (int m = 0; m < 4; ++m) _Pragma("unroll") for (int n = 0; n < 2; ++n) _Pragma("unroll") for (int k = 0; k < 2; ++k) \
;         acc[ai][bj][m][n] = __builtin_amdgcn_mfma_f32_16x16x32_bf16(Bt[n][k], At[m][k], acc[ai][bj][m][n], 0, 0, 0); __builtin_amdgcn_s_setprio(0); } while (0)
; #define PG8_WAIT_V(n) asm volatile("s_waitcnt vmcnt(" #n ")" ::: "memory")
; #define PG8_WAIT_L(n) asm volatile("s_waitcnt lgkmcnt(" #n ")" ::: "memory")
; template <class Epi>
; __device__ __forceinline__ void gemm_phase(LAS unsigned char* lds, const Gemm g, const StaticOrder& S, const Epi& E) {
;     ...
;         for (int t = 0; t < nt; t += 2) {
;             const bool last = (t == nt - 2);
;             const char* a1 = cA + (size_t)(t + 1) * kstep;
;             const char* a2 = last ? nA : cA + (size_t)(t + 2) * kstep; const char* b2 = last ? nB : cB + (size_t)(t + 2) * kstep;
;             const char* a3 = a2 + kstep; const char* b3 = b2 + kstep;
;             PG8_LDB(B0, 0, 0); PG8_SCHED; PG8_LDA(At, 0, 0); PG8_STAGE(PG8_SA(1, 1), a1 + hstep, voffA);
;             PG8_WAIT_L(8); PG8_BAR; PG8_WAIT_L(0); PG8_MMA(0, 0, At, B0); PG8_BAR; PG8_SCHED;
;             PG8_LDB(B1, 0, 1); PG8_STAGE(PG8_SB(0, 0), b2, voffB);
;             PG8_BAR; PG8_WAIT_L(0); PG8_MMA(0, 1, At, B1); PG8_BAR;
;             PG8_LDA(At, 0, 1); PG8_STAGE(PG8_SA(0, 0), a2, voffA);
;             PG8_BAR; PG8_WAIT_L(0); PG8_MMA(1, 0, At, B0); PG8_BAR; PG8_SCHED;
;             PG8_STAGE(PG8_SB(0, 1), b2 + hstep, voffB);
;             PG8_WAIT_V(6); PG8_BAR; PG8_MMA(1, 1, At, B1); PG8_BAR;
.LBB0_119:
	s_add_i32 s41, s16, 2
	s_add_u32 s18, s14, 0x80
	s_addc_u32 s17, s15, 0
	ds_read_b128 v[128:131], v224
	ds_read_b128 v[132:135], v224 offset:1024
	ds_read_b128 v[136:139], v224 offset:2048
	ds_read_b128 v[140:143], v224 offset:3072
	s_cmp_eq_u32 s31, s16
	s_cselect_b32 s16, s10, s18
	s_cselect_b32 s17, s11, s17
	s_cselect_b32 s19, s13, s40
	s_cselect_b32 s18, s12, s39
	s_add_i32 m0, s24, 0xc000
	ds_read_b128 v[144:147], v247
	ds_read_b128 v[148:151], v247 offset:1024
	ds_read_b128 v[152:155], v247 offset:2048
	ds_read_b128 v[156:159], v247 offset:3072
	ds_read_b128 v[160:163], v247 offset:4096
	ds_read_b128 v[164:167], v247 offset:5120
	ds_read_b128 v[168:171], v247 offset:6144
	global_load_lds_dwordx4 v210, s[14:15]
	s_add_i32 m0, s24, 0xe000
	ds_read_b128 v[172:175], v247 offset:7168
	global_load_lds_dwordx4 v208, s[14:15]
	s_waitcnt lgkmcnt(8)
	s_waitcnt vmcnt(10)
	s_barrier
	s_waitcnt lgkmcnt(0)
	v_mfma_f32_16x16x32_bf16 v[124:127], v[128:131], v[144:147], v[124:127]
	v_mfma_f32_16x16x32_bf16 v[120:123], v[136:139], v[144:147], v[120:123]
	v_mfma_f32_16x16x32_bf16 v[108:111], v[128:131], v[152:155], v[108:111]
	v_mfma_f32_16x16x32_bf16 v[104:107], v[136:139], v[152:155], v[104:107]
	v_mfma_f32_16x16x32_bf16 v[92:95], v[128:131], v[160:163], v[92:95]
	v_mfma_f32_16x16x32_bf16 v[88:91], v[136:139], v[160:163], v[88:91]
	v_mfma_f32_16x16x32_bf16 v[76:79], v[128:131], v[168:171], v[76:79]
	v_mfma_f32_16x16x32_bf16 v[72:75], v[136:139], v[168:171], v[72:75]
	v_mfma_f32_16x16x32_bf16 v[124:127], v[132:135], v[148:151], v[124:127]
	v_mfma_f32_16x16x32_bf16 v[120:123], v[140:143], v[148:151], v[120:123]
	v_mfma_f32_16x16x32_bf16 v[108:111], v[132:135], v[156:159], v[108:111]
	v_mfma_f32_16x16x32_bf16 v[104:107], v[140:143], v[156:159], v[104:107]
	v_mfma_f32_16x16x32_bf16 v[92:95], v[132:135], v[164:167], v[92:95]
	v_mfma_f32_16x16x32_bf16 v[88:91], v[140:143], v[164:167], v[88:91]
	v_mfma_f32_16x16x32_bf16 v[76:79], v[132:135], v[172:175], v[76:79]
	v_mfma_f32_16x16x32_bf16 v[72:75], v[140:143], v[172:175], v[72:75]
	s_barrier
	s_add_u32 s80, s18, 0x80
	s_addc_u32 s81, s19, 0
	s_mov_b32 m0, s86
	ds_read_b128 v[176:179], v225
	ds_read_b128 v[180:183], v225 offset:1024
	ds_read_b128 v[184:187], v225 offset:2048
	global_load_lds_dwordx4 v194, s[18:19]
	s_add_i32 m0, s86, 0x2000
	ds_read_b128 v[188:191], v225 offset:3072
	global_load_lds_dwordx4 v206, s[18:19]
	s_waitcnt vmcnt(10)
	s_barrier
	s_waitcnt lgkmcnt(0)
	v_mfma_f32_16x16x32_bf16 v[116:119], v[176:179], v[144:147], v[116:119]
	v_mfma_f32_16x16x32_bf16 v[112:115], v[184:187], v[144:147], v[112:115]
	v_mfma_f32_16x16x32_bf16 v[100:103], v[176:179], v[152:155], v[100:103]
	v_mfma_f32_16x16x32_bf16 v[96:99], v[184:187], v[152:155], v[96:99]
	v_mfma_f32_16x16x32_bf16 v[84:87], v[176:179], v[160:163], v[84:87]
	v_mfma_f32_16x16x32_bf16 v[80:83], v[184:187], v[160:163], v[80:83]
	v_mfma_f32_16x16x32_bf16 v[68:71], v[176:179], v[168:171], v[68:71]
	v_mfma_f32_16x16x32_bf16 v[64:67], v[184:187], v[168:171], v[64:67]
	v_mfma_f32_16x16x32_bf16 v[116:119], v[180:183], v[148:151], v[116:119]
	v_mfma_f32_16x16x32_bf16 v[112:115], v[188:191], v[148:151], v[112:115]
	v_mfma_f32_16x16x32_bf16 v[100:103], v[180:183], v[156:159], v[100:103]
	v_mfma_f32_16x16x32_bf16 v[96:99], v[188:191], v[156:159], v[96:99]
	v_mfma_f32_16x16x32_bf16 v[84:87], v[180:183], v[164:167], v[84:87]
	v_mfma_f32_16x16x32_bf16 v[80:83], v[188:191], v[164:167], v[80:83]
	v_mfma_f32_16x16x32_bf16 v[68:71], v[180:183], v[172:175], v[68:71]
	v_mfma_f32_16x16x32_bf16 v[64:67], v[188:191], v[172:175], v[64:67]
	s_mov_b32 m0, s24
	s_add_u32 s82, s16, 0x80
	s_addc_u32 s83, s17, 0
	s_barrier
	ds_read_b128 v[144:147], v247 offset:16384
	ds_read_b128 v[148:151], v247 offset:17408
	ds_read_b128 v[152:155], v247 offset:18432
	ds_read_b128 v[156:159], v247 offset:19456
	ds_read_b128 v[160:163], v247 offset:20480
	ds_read_b128 v[164:167], v247 offset:21504
	ds_read_b128 v[168:171], v247 offset:22528
	global_load_lds_dwordx4 v202, s[16:17]
	s_mov_b32 m0, s25
	ds_read_b128 v[172:175], v247 offset:23552
	global_load_lds_dwordx4 v204, s[16:17]
	s_barrier
	s_waitcnt lgkmcnt(0)
	v_mfma_f32_16x16x32_bf16 v[60:63], v[128:131], v[144:147], v[60:63]
	v_mfma_f32_16x16x32_bf16 v[56:59], v[136:139], v[144:147], v[56:59]
	v_mfma_f32_16x16x32_bf16 v[44:47], v[128:131], v[152:155], v[44:47]
	v_mfma_f32_16x16x32_bf16 v[40:43], v[136:139], v[152:155], v[40:43]
	v_mfma_f32_16x16x32_bf16 v[28:31], v[128:131], v[160:163], v[28:31]
	v_mfma_f32_16x16x32_bf16 v[24:27], v[136:139], v[160:163], v[24:27]
	v_mfma_f32_16x16x32_bf16 v[12:15], v[128:131], v[168:171], v[12:15]
	v_mfma_f32_16x16x32_bf16 v[8:11], v[136:139], v[168:171], v[8:11]
	v_mfma_f32_16x16x32_bf16 v[60:63], v[132:135], v[148:151], v[60:63]
	v_mfma_f32_16x16x32_bf16 v[56:59], v[140:143], v[148:151], v[56:59]
	v_mfma_f32_16x16x32_bf16 v[44:47], v[132:135], v[156:159], v[44:47]
	v_mfma_f32_16x16x32_bf16 v[40:43], v[140:143], v[156:159], v[40:43]
	v_mfma_f32_16x16x32_bf16 v[28:31], v[132:135], v[164:167], v[28:31]
	v_mfma_f32_16x16x32_bf16 v[24:27], v[140:143], v[164:167], v[24:27]
	v_mfma_f32_16x16x32_bf16 v[12:15], v[132:135], v[172:175], v[12:15]
	v_mfma_f32_16x16x32_bf16 v[8:11], v[140:143], v[172:175], v[8:11]
	s_barrier
	s_add_u32 s18, s18, s0
	s_addc_u32 s19, s19, s1
	s_add_u32 s84, s18, 0x80
	s_mov_b32 m0, s87
	s_addc_u32 s85, s19, 0
	global_load_lds_dwordx4 v194, s[18:19]
	s_add_i32 m0, s87, 0x2000
	s_nop 0
	global_load_lds_dwordx4 v206, s[18:19]
	s_waitcnt vmcnt(10)
	s_barrier
; #define PG8_STAGE(bufoff, gbase, voff) do { _Pragma("unroll") for (int _i = 0; _i < 2; ++_i) \
;         __builtin_amdgcn_global_load_lds((const unsigned*)((const char*)(gbase) + (voff)[_i]), (LAS unsigned*)(lds + (bufoff) + ldsw + _i * 8192), 16, 0, 0); } while (0)
; #define PG8_LDA(dst, b, h) do { _Pragma("unroll") for (int m = 0; m < 4; ++m) _Pragma("unroll") for (int k = 0; k < 2; ++k) dst[m][k] = *(const LAS bf16x8*)(lds + PG8_SA(b, h) + aoff + m * 2048 + k * 1024); } while (0)
; #define PG8_LDB(dst, b, h) do { _Pragma("unroll") for (int n = 0; n < 2; ++n) _Pragma("unroll") for (int k = 0; k < 2; ++k) dst[n][k] = *(const LAS bf16x8*)(lds + PG8_SB(b, h) + boff + n * 2048 + k * 1024); } while (0)
; #define PG8_MMA(ai, bj, At, Bt) do { __builtin_amdgcn_s_setprio(1); _Pragma("unroll") for (int m = 0; m < 4; ++m) _Pragma("unroll") for (int n = 0; n < 2; ++n) _Pragma("unroll") for (int k = 0; k < 2; ++k) \
;         acc[ai][bj][m][n] = __builtin_amdgcn_mfma_f32_16x16x32_bf16(Bt[n][k], At[m][k], acc[ai][bj][m][n], 0, 0, 0); __builtin_amdgcn_s_setprio(0); } while (0)
; #define PG8_WAIT_V(n) asm volatile("s_waitcnt vmcnt(" #n ")" ::: "memory")
; #define PG8_WAIT_L(n) asm volatile("s_waitcnt lgkmcnt(" #n ")" ::: "memory")
; #define PG8_BAR __builtin_amdgcn_s_barrier()
; #define PG8_SCHED __builtin_amdgcn_sched_barrier(0)
; template <class Epi>
; __device__ __forceinline__ void gemm_phase(LAS unsigned char* lds, const Gemm g, const StaticOrder& S, const Epi& E) {
;     ...
;             PG8_WAIT_V(6); PG8_BAR; PG8_MMA(1, 1, At, B1); PG8_BAR;
;             PG8_LDB(B0, 1, 0); PG8_SCHED; PG8_LDA(At, 1, 0); PG8_STAGE(PG8_SA(0, 1), a2 + hstep, voffA);
;             PG8_WAIT_L(8); PG8_BAR; PG8_WAIT_L(0); PG8_MMA(0, 0, At, B0); PG8_BAR; PG8_SCHED;
;             PG8_LDB(B1, 1, 1); PG8_STAGE(PG8_SB(1, 0), b3, voffB);
;             PG8_BAR; PG8_WAIT_L(0); PG8_MMA(0, 1, At, B1); PG8_BAR;
	v_mfma_f32_16x16x32_bf16 v[52:55], v[176:179], v[144:147], v[52:55]
	v_mfma_f32_16x16x32_bf16 v[48:51], v[184:187], v[144:147], v[48:51]
	v_mfma_f32_16x16x32_bf16 v[36:39], v[176:179], v[152:155], v[36:39]
	v_mfma_f32_16x16x32_bf16 v[32:35], v[184:187], v[152:155], v[32:35]
	v_mfma_f32_16x16x32_bf16 v[20:23], v[176:179], v[160:163], v[20:23]
	v_mfma_f32_16x16x32_bf16 v[16:19], v[184:187], v[160:163], v[16:19]
	v_mfma_f32_16x16x32_bf16 v[4:7], v[176:179], v[168:171], v[4:7]
	v_mfma_f32_16x16x32_bf16 v[0:3], v[184:187], v[168:171], v[0:3]
	v_mfma_f32_16x16x32_bf16 v[52:55], v[180:183], v[148:151], v[52:55]
	v_mfma_f32_16x16x32_bf16 v[48:51], v[188:191], v[148:151], v[48:51]
	v_mfma_f32_16x16x32_bf16 v[36:39], v[180:183], v[156:159], v[36:39]
	v_mfma_f32_16x16x32_bf16 v[32:35], v[188:191], v[156:159], v[32:35]
	v_mfma_f32_16x16x32_bf16 v[20:23], v[180:183], v[164:167], v[20:23]
	v_mfma_f32_16x16x32_bf16 v[16:19], v[188:191], v[164:167], v[16:19]
	v_mfma_f32_16x16x32_bf16 v[4:7], v[180:183], v[172:175], v[4:7]
	v_mfma_f32_16x16x32_bf16 v[0:3], v[188:191], v[172:175], v[0:3]
	s_barrier
	ds_read_b128 v[128:131], v226
	ds_read_b128 v[132:135], v226 offset:1024
	ds_read_b128 v[136:139], v226 offset:2048
	ds_read_b128 v[140:143], v226 offset:3072
	s_add_u32 s16, s16, s0
	s_addc_u32 s17, s17, s1
	s_mov_b32 m0, s26
	ds_read_b128 v[144:147], v247 offset:32768
	ds_read_b128 v[148:151], v247 offset:33792
	ds_read_b128 v[152:155], v247 offset:34816
	ds_read_b128 v[156:159], v247 offset:35840
	ds_read_b128 v[160:163], v247 offset:36864
	ds_read_b128 v[164:167], v247 offset:37888
	ds_read_b128 v[168:171], v247 offset:38912
	global_load_lds_dwordx4 v202, s[16:17]
	s_mov_b32 m0, s27
	ds_read_b128 v[172:175], v247 offset:39936
	global_load_lds_dwordx4 v204, s[16:17]
	s_waitcnt lgkmcnt(8)
	s_waitcnt vmcnt(10)
	s_barrier
	s_waitcnt lgkmcnt(0)
	v_mfma_f32_16x16x32_bf16 v[124:127], v[128:131], v[144:147], v[124:127]
	v_mfma_f32_16x16x32_bf16 v[120:123], v[136:139], v[144:147], v[120:123]
	v_mfma_f32_16x16x32_bf16 v[108:111], v[128:131], v[152:155], v[108:111]
	v_mfma_f32_16x16x32_bf16 v[104:107], v[136:139], v[152:155], v[104:107]
	v_mfma_f32_16x16x32_bf16 v[92:95], v[128:131], v[160:163], v[92:95]
	v_mfma_f32_16x16x32_bf16 v[88:91], v[136:139], v[160:163], v[88:91]
	v_mfma_f32_16x16x32_bf16 v[76:79], v[128:131], v[168:171], v[76:79]
	v_mfma_f32_16x16x32_bf16 v[72:75], v[136:139], v[168:171], v[72:75]
	v_mfma_f32_16x16x32_bf16 v[124:127], v[132:135], v[148:151], v[124:127]
	v_mfma_f32_16x16x32_bf16 v[120:123], v[140:143], v[148:151], v[120:123]
	v_mfma_f32_16x16x32_bf16 v[108:111], v[132:135], v[156:159], v[108:111]
	v_mfma_f32_16x16x32_bf16 v[104:107], v[140:143], v[156:159], v[104:107]
	v_mfma_f32_16x16x32_bf16 v[92:95], v[132:135], v[164:167], v[92:95]
	v_mfma_f32_16x16x32_bf16 v[88:91], v[140:143], v[164:167], v[88:91]
	v_mfma_f32_16x16x32_bf16 v[76:79], v[132:135], v[172:175], v[76:79]
	v_mfma_f32_16x16x32_bf16 v[72:75], v[140:143], v[172:175], v[72:75]
	s_barrier
	s_mov_b32 m0, s88
	ds_read_b128 v[176:179], v227
	ds_read_b128 v[180:183], v227 offset:1024
	ds_read_b128 v[184:187], v227 offset:2048
	global_load_lds_dwordx4 v194, s[80:81]
	s_add_i32 m0, s88, 0x2000
	ds_read_b128 v[188:191], v227 offset:3072
	global_load_lds_dwordx4 v206, s[80:81]
	s_waitcnt vmcnt(10)
	s_barrier
; #define PG8_STAGE(bufoff, gbase, voff) do { _Pragma("unroll") for (int _i = 0; _i < 2; ++_i) \
;         __builtin_amdgcn_global_load_lds((const unsigned*)((const char*)(gbase) + (voff)[_i]), (LAS unsigned*)(lds + (bufoff) + ldsw + _i * 8192), 16, 0, 0); } while (0)
; #define PG8_LDA(dst, b, h) do { _Pragma("unroll") for (int m = 0; m < 4; ++m) _Pragma("unroll") for (int k = 0; k < 2; ++k) dst[m][k] = *(const LAS bf16x8*)(lds + PG8_SA(b, h) + aoff + m * 2048 + k * 1024); } while (0)
; #define PG8_MMA(ai, bj, At, Bt) do { __builtin_amdgcn_s_setprio(1); _Pragma("unroll") for (int m = 0; m < 4; ++m) _Pragma("unroll") for (int n = 0; n < 2; ++n) _Pragma("unroll") for (int k = 0; k < 2; ++k) \
;         acc[ai][bj][m][n] = __builtin_amdgcn_mfma_f32_16x16x32_bf16(Bt[n][k], At[m][k], acc[ai][bj][m][n], 0, 0, 0); __builtin_amdgcn_s_setprio(0); } while (0)
; #define PG8_WAIT_V(n) asm volatile("s_waitcnt vmcnt(" #n ")" ::: "memory")
; #define PG8_WAIT_L(n) asm volatile("s_waitcnt lgkmcnt(" #n ")" ::: "memory")
; #define PG8_BAR __builtin_amdgcn_s_barrier()
; #define PG8_SCHED __builtin_amdgcn_sched_barrier(0)
; template <class Epi>
; __device__ __forceinline__ void gemm_phase(LAS unsigned char* lds, const Gemm g, const StaticOrder& S, const Epi& E) {
;     ...
;             PG8_BAR; PG8_WAIT_L(0); PG8_MMA(0, 1, At, B1); PG8_BAR;
;             PG8_LDA(At, 1, 1); PG8_STAGE(PG8_SA(1, 0), a3, voffA);
;             PG8_BAR; PG8_WAIT_L(0); PG8_MMA(1, 0, At, B0); PG8_BAR; PG8_SCHED;
;             PG8_STAGE(PG8_SB(1, 1), b3 + hstep, voffB);
;             PG8_WAIT_V(6); PG8_BAR; PG8_MMA(1, 1, At, B1); PG8_BAR;
	s_waitcnt lgkmcnt(0)
	v_mfma_f32_16x16x32_bf16 v[116:119], v[176:179], v[144:147], v[116:119]
	v_mfma_f32_16x16x32_bf16 v[112:115], v[184:187], v[144:147], v[112:115]
	v_mfma_f32_16x16x32_bf16 v[100:103], v[176:179], v[152:155], v[100:103]
	v_mfma_f32_16x16x32_bf16 v[96:99], v[184:187], v[152:155], v[96:99]
	v_mfma_f32_16x16x32_bf16 v[84:87], v[176:179], v[160:163], v[84:87]
	v_mfma_f32_16x16x32_bf16 v[80:83], v[184:187], v[160:163], v[80:83]
	v_mfma_f32_16x16x32_bf16 v[68:71], v[176:179], v[168:171], v[68:71]
	v_mfma_f32_16x16x32_bf16 v[64:67], v[184:187], v[168:171], v[64:67]
	v_mfma_f32_16x16x32_bf16 v[116:119], v[180:183], v[148:151], v[116:119]
	v_mfma_f32_16x16x32_bf16 v[112:115], v[188:191], v[148:151], v[112:115]
	v_mfma_f32_16x16x32_bf16 v[100:103], v[180:183], v[156:159], v[100:103]
	v_mfma_f32_16x16x32_bf16 v[96:99], v[188:191], v[156:159], v[96:99]
	v_mfma_f32_16x16x32_bf16 v[84:87], v[180:183], v[164:167], v[84:87]
	v_mfma_f32_16x16x32_bf16 v[80:83], v[188:191], v[164:167], v[80:83]
	v_mfma_f32_16x16x32_bf16 v[68:71], v[180:183], v[172:175], v[68:71]
	v_mfma_f32_16x16x32_bf16 v[64:67], v[188:191], v[172:175], v[64:67]
	s_mov_b32 m0, s28
	s_barrier
	ds_read_b128 v[144:147], v247 offset:49152
	ds_read_b128 v[148:151], v247 offset:50176
	ds_read_b128 v[152:155], v247 offset:51200
	ds_read_b128 v[156:159], v247 offset:52224
	ds_read_b128 v[160:163], v247 offset:53248
	ds_read_b128 v[164:167], v247 offset:54272
	ds_read_b128 v[168:171], v247 offset:55296
	global_load_lds_dwordx4 v202, s[82:83]
	s_mov_b32 m0, s29
	ds_read_b128 v[172:175], v247 offset:56320
	global_load_lds_dwordx4 v204, s[82:83]
	s_barrier
	s_waitcnt lgkmcnt(0)
	v_mfma_f32_16x16x32_bf16 v[60:63], v[128:131], v[144:147], v[60:63]
	v_mfma_f32_16x16x32_bf16 v[56:59], v[136:139], v[144:147], v[56:59]
	v_mfma_f32_16x16x32_bf16 v[44:47], v[128:131], v[152:155], v[44:47]
	v_mfma_f32_16x16x32_bf16 v[40:43], v[136:139], v[152:155], v[40:43]
	v_mfma_f32_16x16x32_bf16 v[28:31], v[128:131], v[160:163], v[28:31]
	v_mfma_f32_16x16x32_bf16 v[24:27], v[136:139], v[160:163], v[24:27]
	v_mfma_f32_16x16x32_bf16 v[12:15], v[128:131], v[168:171], v[12:15]
	v_mfma_f32_16x16x32_bf16 v[8:11], v[136:139], v[168:171], v[8:11]
	v_mfma_f32_16x16x32_bf16 v[60:63], v[132:135], v[148:151], v[60:63]
	v_mfma_f32_16x16x32_bf16 v[56:59], v[140:143], v[148:151], v[56:59]
	v_mfma_f32_16x16x32_bf16 v[44:47], v[132:135], v[156:159], v[44:47]
	v_mfma_f32_16x16x32_bf16 v[40:43], v[140:143], v[156:159], v[40:43]
	v_mfma_f32_16x16x32_bf16 v[28:31], v[132:135], v[164:167], v[28:31]
	v_mfma_f32_16x16x32_bf16 v[24:27], v[140:143], v[164:167], v[24:27]
	v_mfma_f32_16x16x32_bf16 v[12:15], v[132:135], v[172:175], v[12:15]
	v_mfma_f32_16x16x32_bf16 v[8:11], v[140:143], v[172:175], v[8:11]
	s_barrier
	s_mov_b32 m0, s89
	s_nop 0
	global_load_lds_dwordx4 v194, s[84:85]
	s_add_i32 m0, s89, 0x2000
	s_nop 0
	global_load_lds_dwordx4 v206, s[84:85]
	s_waitcnt vmcnt(10)
	s_barrier
	v_mfma_f32_16x16x32_bf16 v[52:55], v[176:179], v[144:147], v[52:55]
	v_mfma_f32_16x16x32_bf16 v[48:51], v[184:187], v[144:147], v[48:51]
	v_mfma_f32_16x16x32_bf16 v[36:39], v[176:179], v[152:155], v[36:39]
	v_mfma_f32_16x16x32_bf16 v[32:35], v[184:187], v[152:155], v[32:35]
	v_mfma_f32_16x16x32_bf16 v[20:23], v[176:179], v[160:163], v[20:23]
	v_mfma_f32_16x16x32_bf16 v[16:19], v[184:187], v[160:163], v[16:19]
	v_mfma_f32_16x16x32_bf16 v[4:7], v[176:179], v[168:171], v[4:7]
	v_mfma_f32_16x16x32_bf16 v[0:3], v[184:187], v[168:171], v[0:3]
	v_mfma_f32_16x16x32_bf16 v[52:55], v[180:183], v[148:151], v[52:55]
	v_mfma_f32_16x16x32_bf16 v[48:51], v[188:191], v[148:151], v[48:51]
	v_mfma_f32_16x16x32_bf16 v[36:39], v[180:183], v[156:159], v[36:39]
	v_mfma_f32_16x16x32_bf16 v[32:35], v[188:191], v[156:159], v[32:35]
	v_mfma_f32_16x16x32_bf16 v[20:23], v[180:183], v[164:167], v[20:23]
	v_mfma_f32_16x16x32_bf16 v[16:19], v[188:191], v[164:167], v[16:19]
	v_mfma_f32_16x16x32_bf16 v[4:7], v[180:183], v[172:175], v[4:7]
	v_mfma_f32_16x16x32_bf16 v[0:3], v[188:191], v[172:175], v[0:3]
	s_add_u32 s39, s39, 0x100
	s_addc_u32 s40, s40, 0
	s_add_u32 s14, s14, 0x100
	s_addc_u32 s15, s15, 0
	s_cmp_ge_i32 s41, s30
	s_mov_b32 s16, s41
	s_barrier
	s_cbranch_scc0 .LBB0_119

; #define PG8_STAGE(bufoff, gbase, voff) do { _Pragma("unroll") for (int _i = 0; _i < 2; ++_i) \
;         __builtin_amdgcn_global_load_lds((const unsigned*)((const char*)(gbase) + (voff)[_i]), (LAS unsigned*)(lds + (bufoff) + ldsw + _i * 8192), 16, 0, 0); } while (0)
; #define PG8_LDA(dst, b, h) do { _Pragma("unroll") for (int m = 0; m < 4; ++m) _Pragma("unroll") for (int k = 0; k < 2; ++k) dst[m][k] = *(const LAS bf16x8*)(lds + PG8_SA(b, h) + aoff + m * 2048 + k * 1024); } while (0)
; #define PG8_LDB(dst, b, h) do { _Pragma("unroll") for (int n = 0; n < 2; ++n) _Pragma("unroll") for (int k = 0; k < 2; ++k) dst[n][k] = *(const LAS bf16x8*)(lds + PG8_SB(b, h) + boff + n * 2048 + k * 1024); } while (0)
; #define PG8_MMA(ai, bj, At, Bt) do { __builtin_amdgcn_s_setprio(1); _Pragma("unroll") for (int m = 0; m < 4; ++m) _Pragma("unroll") for (int n = 0; n < 2; ++n) _Pragma("unroll") for (int k = 0; k < 2; ++k) \
;         acc[ai][bj][m][n] = __builtin_amdgcn_mfma_f32_16x16x32_bf16(Bt[n][k], At[m][k], acc[ai][bj][m][n], 0, 0, 0); __builtin_amdgcn_s_setprio(0); } while (0)
; #define PG8_WAIT_V(n) asm volatile("s_waitcnt vmcnt(" #n ")" ::: "memory")
; #define PG8_WAIT_L(n) asm volatile("s_waitcnt lgkmcnt(" #n ")" ::: "memory")
; template <class Epi>
; __device__ __forceinline__ void gemm_phase(LAS unsigned char* lds, const Gemm g, const StaticOrder& S, const Epi& E) {
;     ...
;         for (int t = 0; t < nt; t += 2) {
;             const bool last = (t == nt - 2);
;             const char* a1 = cA + (size_t)(t + 1) * kstep;
;             const char* a2 = last ? nA : cA + (size_t)(t + 2) * kstep; const char* b2 = last ? nB : cB + (size_t)(t + 2) * kstep;
;             const char* a3 = a2 + kstep; const char* b3 = b2 + kstep;
;             PG8_LDB(B0, 0, 0); PG8_SCHED; PG8_LDA(At, 0, 0); PG8_STAGE(PG8_SA(1, 1), a1 + hstep, voffA);
;             PG8_WAIT_L(8); PG8_BAR; PG8_WAIT_L(0); PG8_MMA(0, 0, At, B0); PG8_BAR; PG8_SCHED;
;             PG8_LDB(B1, 0, 1); PG8_STAGE(PG8_SB(0, 0), b2, voffB);
;             PG8_BAR; PG8_WAIT_L(0); PG8_MMA(0, 1, At, B1); PG8_BAR;
;             PG8_LDA(At, 0, 1); PG8_STAGE(PG8_SA(0, 0), a2, voffA);
;             PG8_BAR; PG8_WAIT_L(0); PG8_MMA(1, 0, At, B0); PG8_BAR; PG8_SCHED;
;             PG8_STAGE(PG8_SB(0, 1), b2 + hstep, voffB);
;             PG8_WAIT_V(6); PG8_BAR; PG8_MMA(1, 1, At, B1); PG8_BAR;
.LBB0_165:
	s_add_i32 s44, s18, 2
	s_add_u32 s20, s16, 0x80
	s_addc_u32 s19, s17, 0
	ds_read_b128 v[138:141], v224
	ds_read_b128 v[152:155], v224 offset:1024
	ds_read_b128 v[156:159], v224 offset:2048
	ds_read_b128 v[160:163], v224 offset:3072
	s_cmp_eq_u32 s35, s18
	s_cselect_b32 s18, s10, s20
	s_cselect_b32 s19, s11, s19
	s_cselect_b32 s21, s13, s43
	s_cselect_b32 s20, s12, s42
	s_add_i32 m0, s27, 0xc000
	ds_read_b128 v[164:167], v150
	ds_read_b128 v[168:171], v150 offset:1024
	ds_read_b128 v[172:175], v150 offset:2048
	ds_read_b128 v[176:179], v150 offset:3072
	ds_read_b128 v[180:183], v150 offset:4096
	ds_read_b128 v[184:187], v150 offset:5120
	ds_read_b128 v[188:191], v150 offset:6144
	global_load_lds_dwordx4 v136, s[16:17]
	s_add_i32 m0, s27, 0xe000
	ds_read_b128 v[202:205], v150 offset:7168
	global_load_lds_dwordx4 v134, s[16:17]
	s_waitcnt lgkmcnt(8)
	s_waitcnt vmcnt(10)
	s_barrier
	s_waitcnt lgkmcnt(0)
	v_mfma_f32_16x16x32_bf16 v[124:127], v[138:141], v[164:167], v[124:127]
	v_mfma_f32_16x16x32_bf16 v[120:123], v[156:159], v[164:167], v[120:123]
	v_mfma_f32_16x16x32_bf16 v[108:111], v[138:141], v[172:175], v[108:111]
	v_mfma_f32_16x16x32_bf16 v[104:107], v[156:159], v[172:175], v[104:107]
	v_mfma_f32_16x16x32_bf16 v[92:95], v[138:141], v[180:183], v[92:95]
	v_mfma_f32_16x16x32_bf16 v[88:91], v[156:159], v[180:183], v[88:91]
	v_mfma_f32_16x16x32_bf16 v[76:79], v[138:141], v[188:191], v[76:79]
	v_mfma_f32_16x16x32_bf16 v[72:75], v[156:159], v[188:191], v[72:75]
	v_mfma_f32_16x16x32_bf16 v[124:127], v[152:155], v[168:171], v[124:127]
	v_mfma_f32_16x16x32_bf16 v[120:123], v[160:163], v[168:171], v[120:123]
	v_mfma_f32_16x16x32_bf16 v[108:111], v[152:155], v[176:179], v[108:111]
	v_mfma_f32_16x16x32_bf16 v[104:107], v[160:163], v[176:179], v[104:107]
	v_mfma_f32_16x16x32_bf16 v[92:95], v[152:155], v[184:187], v[92:95]
	v_mfma_f32_16x16x32_bf16 v[88:91], v[160:163], v[184:187], v[88:91]
	v_mfma_f32_16x16x32_bf16 v[76:79], v[152:155], v[202:205], v[76:79]
	v_mfma_f32_16x16x32_bf16 v[72:75], v[160:163], v[202:205], v[72:75]
	s_barrier
	ds_read_b128 v[206:209], v225
	ds_read_b128 v[210:213], v225 offset:1024
	s_add_u32 s80, s20, 0x80
	s_addc_u32 s81, s21, 0
	s_mov_b32 m0, s86
	ds_read_b128 v[218:221], v225 offset:3072
	global_load_lds_dwordx4 v194, s[20:21]
	s_add_i32 m0, s86, 0x2000
	ds_read_b128 v[214:217], v225 offset:2048
	global_load_lds_dwordx4 v132, s[20:21]
	s_waitcnt vmcnt(10)
	s_barrier
	s_waitcnt lgkmcnt(0)
	v_mfma_f32_16x16x32_bf16 v[116:119], v[206:209], v[164:167], v[116:119]
	v_mfma_f32_16x16x32_bf16 v[112:115], v[214:217], v[164:167], v[112:115]
	v_mfma_f32_16x16x32_bf16 v[100:103], v[206:209], v[172:175], v[100:103]
	v_mfma_f32_16x16x32_bf16 v[96:99], v[214:217], v[172:175], v[96:99]
	v_mfma_f32_16x16x32_bf16 v[84:87], v[206:209], v[180:183], v[84:87]
	v_mfma_f32_16x16x32_bf16 v[80:83], v[214:217], v[180:183], v[80:83]
	v_mfma_f32_16x16x32_bf16 v[68:71], v[206:209], v[188:191], v[68:71]
	v_mfma_f32_16x16x32_bf16 v[64:67], v[214:217], v[188:191], v[64:67]
	v_mfma_f32_16x16x32_bf16 v[116:119], v[210:213], v[168:171], v[116:119]
	v_mfma_f32_16x16x32_bf16 v[112:115], v[218:221], v[168:171], v[112:115]
	v_mfma_f32_16x16x32_bf16 v[100:103], v[210:213], v[176:179], v[100:103]
	v_mfma_f32_16x16x32_bf16 v[96:99], v[218:221], v[176:179], v[96:99]
	v_mfma_f32_16x16x32_bf16 v[84:87], v[210:213], v[184:187], v[84:87]
	v_mfma_f32_16x16x32_bf16 v[80:83], v[218:221], v[184:187], v[80:83]
	v_mfma_f32_16x16x32_bf16 v[68:71], v[210:213], v[202:205], v[68:71]
	v_mfma_f32_16x16x32_bf16 v[64:67], v[218:221], v[202:205], v[64:67]
	s_mov_b32 m0, s27
	s_add_u32 s82, s18, 0x80
	s_addc_u32 s83, s19, 0
	s_barrier
	ds_read_b128 v[164:167], v150 offset:16384
	ds_read_b128 v[168:171], v150 offset:17408
	ds_read_b128 v[172:175], v150 offset:18432
	ds_read_b128 v[176:179], v150 offset:19456
	ds_read_b128 v[180:183], v150 offset:20480
	ds_read_b128 v[184:187], v150 offset:21504
	ds_read_b128 v[188:191], v150 offset:22528
	global_load_lds_dwordx4 v128, s[18:19]
	s_mov_b32 m0, s28
	ds_read_b128 v[202:205], v150 offset:23552
	global_load_lds_dwordx4 v130, s[18:19]
	s_barrier
	s_waitcnt lgkmcnt(0)
	v_mfma_f32_16x16x32_bf16 v[60:63], v[138:141], v[164:167], v[60:63]
	v_mfma_f32_16x16x32_bf16 v[56:59], v[156:159], v[164:167], v[56:59]
	v_mfma_f32_16x16x32_bf16 v[44:47], v[138:141], v[172:175], v[44:47]
	v_mfma_f32_16x16x32_bf16 v[40:43], v[156:159], v[172:175], v[40:43]
	v_mfma_f32_16x16x32_bf16 v[28:31], v[138:141], v[180:183], v[28:31]
	v_mfma_f32_16x16x32_bf16 v[24:27], v[156:159], v[180:183], v[24:27]
	v_mfma_f32_16x16x32_bf16 v[12:15], v[138:141], v[188:191], v[12:15]
	v_mfma_f32_16x16x32_bf16 v[8:11], v[156:159], v[188:191], v[8:11]
	v_mfma_f32_16x16x32_bf16 v[60:63], v[152:155], v[168:171], v[60:63]
	v_mfma_f32_16x16x32_bf16 v[56:59], v[160:163], v[168:171], v[56:59]
	v_mfma_f32_16x16x32_bf16 v[44:47], v[152:155], v[176:179], v[44:47]
	v_mfma_f32_16x16x32_bf16 v[40:43], v[160:163], v[176:179], v[40:43]
	v_mfma_f32_16x16x32_bf16 v[28:31], v[152:155], v[184:187], v[28:31]
	v_mfma_f32_16x16x32_bf16 v[24:27], v[160:163], v[184:187], v[24:27]
	v_mfma_f32_16x16x32_bf16 v[12:15], v[152:155], v[202:205], v[12:15]
	v_mfma_f32_16x16x32_bf16 v[8:11], v[160:163], v[202:205], v[8:11]
	s_barrier
	s_add_u32 s20, s20, s2
	s_addc_u32 s21, s21, s3
	s_add_u32 s84, s20, 0x80
	s_mov_b32 m0, s87
	s_addc_u32 s85, s21, 0
	global_load_lds_dwordx4 v194, s[20:21]
	s_add_i32 m0, s87, 0x2000
	s_nop 0
	global_load_lds_dwordx4 v132, s[20:21]
	s_waitcnt vmcnt(10)
	s_barrier
; #define PG8_STAGE(bufoff, gbase, voff) do { _Pragma("unroll") for (int _i = 0; _i < 2; ++_i) \
;         __builtin_amdgcn_global_load_lds((const unsigned*)((const char*)(gbase) + (voff)[_i]), (LAS unsigned*)(lds + (bufoff) + ldsw + _i * 8192), 16, 0, 0); } while (0)
; #define PG8_LDA(dst, b, h) do { _Pragma("unroll") for (int m = 0; m < 4; ++m) _Pragma("unroll") for (int k = 0; k < 2; ++k) dst[m][k] = *(const LAS bf16x8*)(lds + PG8_SA(b, h) + aoff + m * 2048 + k * 1024); } while (0)
; #define PG8_LDB(dst, b, h) do { _Pragma("unroll") for (int n = 0; n < 2; ++n) _Pragma("unroll") for (int k = 0; k < 2; ++k) dst[n][k] = *(const LAS bf16x8*)(lds + PG8_SB(b, h) + boff + n * 2048 + k * 1024); } while (0)
; #define PG8_MMA(ai, bj, At, Bt) do { __builtin_amdgcn_s_setprio(1); _Pragma("unroll") for (int m = 0; m < 4; ++m) _Pragma("unroll") for (int n = 0; n < 2; ++n) _Pragma("unroll") for (int k = 0; k < 2; ++k) \
;         acc[ai][bj][m][n] = __builtin_amdgcn_mfma_f32_16x16x32_bf16(Bt[n][k], At[m][k], acc[ai][bj][m][n], 0, 0, 0); __builtin_amdgcn_s_setprio(0); } while (0)
; #define PG8_WAIT_V(n) asm volatile("s_waitcnt vmcnt(" #n ")" ::: "memory")
; #define PG8_WAIT_L(n) asm volatile("s_waitcnt lgkmcnt(" #n ")" ::: "memory")
; #define PG8_BAR __builtin_amdgcn_s_barrier()
; #define PG8_SCHED __builtin_amdgcn_sched_barrier(0)
; template <class Epi>
; __device__ __forceinline__ void gemm_phase(LAS unsigned char* lds, const Gemm g, const StaticOrder& S, const Epi& E) {
;     ...
;             PG8_WAIT_V(6); PG8_BAR; PG8_MMA(1, 1, At, B1); PG8_BAR;
;             PG8_LDB(B0, 1, 0); PG8_SCHED; PG8_LDA(At, 1, 0); PG8_STAGE(PG8_SA(0, 1), a2 + hstep, voffA);
;             PG8_WAIT_L(8); PG8_BAR; PG8_WAIT_L(0); PG8_MMA(0, 0, At, B0); PG8_BAR; PG8_SCHED;
;             PG8_LDB(B1, 1, 1); PG8_STAGE(PG8_SB(1, 0), b3, voffB);
;             PG8_BAR; PG8_WAIT_L(0); PG8_MMA(0, 1, At, B1); PG8_BAR;
	v_mfma_f32_16x16x32_bf16 v[52:55], v[206:209], v[164:167], v[52:55]
	v_mfma_f32_16x16x32_bf16 v[48:51], v[214:217], v[164:167], v[48:51]
	v_mfma_f32_16x16x32_bf16 v[36:39], v[206:209], v[172:175], v[36:39]
	v_mfma_f32_16x16x32_bf16 v[32:35], v[214:217], v[172:175], v[32:35]
	v_mfma_f32_16x16x32_bf16 v[20:23], v[206:209], v[180:183], v[20:23]
	v_mfma_f32_16x16x32_bf16 v[16:19], v[214:217], v[180:183], v[16:19]
	v_mfma_f32_16x16x32_bf16 v[4:7], v[206:209], v[188:191], v[4:7]
	v_mfma_f32_16x16x32_bf16 v[0:3], v[214:217], v[188:191], v[0:3]
	v_mfma_f32_16x16x32_bf16 v[52:55], v[210:213], v[168:171], v[52:55]
	v_mfma_f32_16x16x32_bf16 v[48:51], v[218:221], v[168:171], v[48:51]
	v_mfma_f32_16x16x32_bf16 v[36:39], v[210:213], v[176:179], v[36:39]
	v_mfma_f32_16x16x32_bf16 v[32:35], v[218:221], v[176:179], v[32:35]
	v_mfma_f32_16x16x32_bf16 v[20:23], v[210:213], v[184:187], v[20:23]
	v_mfma_f32_16x16x32_bf16 v[16:19], v[218:221], v[184:187], v[16:19]
	v_mfma_f32_16x16x32_bf16 v[4:7], v[210:213], v[202:205], v[4:7]
	v_mfma_f32_16x16x32_bf16 v[0:3], v[218:221], v[202:205], v[0:3]
	s_barrier
	ds_read_b128 v[138:141], v226
	ds_read_b128 v[152:155], v226 offset:1024
	ds_read_b128 v[156:159], v226 offset:2048
	ds_read_b128 v[160:163], v226 offset:3072
	s_add_u32 s18, s18, s2
	s_addc_u32 s19, s19, s3
	s_mov_b32 m0, s29
	ds_read_b128 v[164:167], v150 offset:32768
	ds_read_b128 v[168:171], v150 offset:33792
	ds_read_b128 v[172:175], v150 offset:34816
	ds_read_b128 v[176:179], v150 offset:35840
	ds_read_b128 v[180:183], v150 offset:36864
	ds_read_b128 v[184:187], v150 offset:37888
	ds_read_b128 v[188:191], v150 offset:38912
	global_load_lds_dwordx4 v128, s[18:19]
	s_mov_b32 m0, s30
	ds_read_b128 v[202:205], v150 offset:39936
	global_load_lds_dwordx4 v130, s[18:19]
	s_waitcnt lgkmcnt(8)
	s_waitcnt vmcnt(10)
	s_barrier
	s_waitcnt lgkmcnt(0)
	v_mfma_f32_16x16x32_bf16 v[124:127], v[138:141], v[164:167], v[124:127]
	v_mfma_f32_16x16x32_bf16 v[120:123], v[156:159], v[164:167], v[120:123]
	v_mfma_f32_16x16x32_bf16 v[108:111], v[138:141], v[172:175], v[108:111]
	v_mfma_f32_16x16x32_bf16 v[104:107], v[156:159], v[172:175], v[104:107]
	v_mfma_f32_16x16x32_bf16 v[92:95], v[138:141], v[180:183], v[92:95]
	v_mfma_f32_16x16x32_bf16 v[88:91], v[156:159], v[180:183], v[88:91]
	v_mfma_f32_16x16x32_bf16 v[76:79], v[138:141], v[188:191], v[76:79]
	v_mfma_f32_16x16x32_bf16 v[72:75], v[156:159], v[188:191], v[72:75]
	v_mfma_f32_16x16x32_bf16 v[124:127], v[152:155], v[168:171], v[124:127]
	v_mfma_f32_16x16x32_bf16 v[120:123], v[160:163], v[168:171], v[120:123]
	v_mfma_f32_16x16x32_bf16 v[108:111], v[152:155], v[176:179], v[108:111]
	v_mfma_f32_16x16x32_bf16 v[104:107], v[160:163], v[176:179], v[104:107]
	v_mfma_f32_16x16x32_bf16 v[92:95], v[152:155], v[184:187], v[92:95]
	v_mfma_f32_16x16x32_bf16 v[88:91], v[160:163], v[184:187], v[88:91]
	v_mfma_f32_16x16x32_bf16 v[76:79], v[152:155], v[202:205], v[76:79]
	v_mfma_f32_16x16x32_bf16 v[72:75], v[160:163], v[202:205], v[72:75]
	s_barrier
	s_mov_b32 m0, s88
	ds_read_b128 v[206:209], v227
	ds_read_b128 v[210:213], v227 offset:1024
	ds_read_b128 v[214:217], v227 offset:2048
	global_load_lds_dwordx4 v194, s[80:81]
	s_add_i32 m0, s88, 0x2000
	ds_read_b128 v[218:221], v227 offset:3072
	global_load_lds_dwordx4 v132, s[80:81]
	s_waitcnt vmcnt(10)
	s_barrier
; #define PG8_STAGE(bufoff, gbase, voff) do { _Pragma("unroll") for (int _i = 0; _i < 2; ++_i) \
;         __builtin_amdgcn_global_load_lds((const unsigned*)((const char*)(gbase) + (voff)[_i]), (LAS unsigned*)(lds + (bufoff) + ldsw + _i * 8192), 16, 0, 0); } while (0)
; #define PG8_LDA(dst, b, h) do { _Pragma("unroll") for (int m = 0; m < 4; ++m) _Pragma("unroll") for (int k = 0; k < 2; ++k) dst[m][k] = *(const LAS bf16x8*)(lds + PG8_SA(b, h) + aoff + m * 2048 + k * 1024); } while (0)
; #define PG8_MMA(ai, bj, At, Bt) do { __builtin_amdgcn_s_setprio(1); _Pragma("unroll") for (int m = 0; m < 4; ++m) _Pragma("unroll") for (int n = 0; n < 2; ++n) _Pragma("unroll") for (int k = 0; k < 2; ++k) \
;         acc[ai][bj][m][n] = __builtin_amdgcn_mfma_f32_16x16x32_bf16(Bt[n][k], At[m][k], acc[ai][bj][m][n], 0, 0, 0); __builtin_amdgcn_s_setprio(0); } while (0)
; #define PG8_WAIT_V(n) asm volatile("s_waitcnt vmcnt(" #n ")" ::: "memory")
; #define PG8_WAIT_L(n) asm volatile("s_waitcnt lgkmcnt(" #n ")" ::: "memory")
; #define PG8_BAR __builtin_amdgcn_s_barrier()
; #define PG8_SCHED __builtin_amdgcn_sched_barrier(0)
; template <class Epi>
; __device__ __forceinline__ void gemm_phase(LAS unsigned char* lds, const Gemm g, const StaticOrder& S, const Epi& E) {
;     ...
;             PG8_BAR; PG8_WAIT_L(0); PG8_MMA(0, 1, At, B1); PG8_BAR;
;             PG8_LDA(At, 1, 1); PG8_STAGE(PG8_SA(1, 0), a3, voffA);
;             PG8_BAR; PG8_WAIT_L(0); PG8_MMA(1, 0, At, B0); PG8_BAR; PG8_SCHED;
;             PG8_STAGE(PG8_SB(1, 1), b3 + hstep, voffB);
;             PG8_WAIT_V(6); PG8_BAR; PG8_MMA(1, 1, At, B1); PG8_BAR;
	s_waitcnt lgkmcnt(0)
	v_mfma_f32_16x16x32_bf16 v[116:119], v[206:209], v[164:167], v[116:119]
	v_mfma_f32_16x16x32_bf16 v[112:115], v[214:217], v[164:167], v[112:115]
	v_mfma_f32_16x16x32_bf16 v[100:103], v[206:209], v[172:175], v[100:103]
	v_mfma_f32_16x16x32_bf16 v[96:99], v[214:217], v[172:175], v[96:99]
	v_mfma_f32_16x16x32_bf16 v[84:87], v[206:209], v[180:183], v[84:87]
	v_mfma_f32_16x16x32_bf16 v[80:83], v[214:217], v[180:183], v[80:83]
	v_mfma_f32_16x16x32_bf16 v[68:71], v[206:209], v[188:191], v[68:71]
	v_mfma_f32_16x16x32_bf16 v[64:67], v[214:217], v[188:191], v[64:67]
	v_mfma_f32_16x16x32_bf16 v[116:119], v[210:213], v[168:171], v[116:119]
	v_mfma_f32_16x16x32_bf16 v[112:115], v[218:221], v[168:171], v[112:115]
	v_mfma_f32_16x16x32_bf16 v[100:103], v[210:213], v[176:179], v[100:103]
	v_mfma_f32_16x16x32_bf16 v[96:99], v[218:221], v[176:179], v[96:99]
	v_mfma_f32_16x16x32_bf16 v[84:87], v[210:213], v[184:187], v[84:87]
	v_mfma_f32_16x16x32_bf16 v[80:83], v[218:221], v[184:187], v[80:83]
	v_mfma_f32_16x16x32_bf16 v[68:71], v[210:213], v[202:205], v[68:71]
	v_mfma_f32_16x16x32_bf16 v[64:67], v[218:221], v[202:205], v[64:67]
	s_mov_b32 m0, s31
	s_barrier
	ds_read_b128 v[164:167], v150 offset:49152
	ds_read_b128 v[168:171], v150 offset:50176
	ds_read_b128 v[172:175], v150 offset:51200
	ds_read_b128 v[176:179], v150 offset:52224
	ds_read_b128 v[180:183], v150 offset:53248
	ds_read_b128 v[184:187], v150 offset:54272
	ds_read_b128 v[188:191], v150 offset:55296
	global_load_lds_dwordx4 v128, s[82:83]
	s_mov_b32 m0, s33
	ds_read_b128 v[202:205], v150 offset:56320
	global_load_lds_dwordx4 v130, s[82:83]
	s_barrier
	s_waitcnt lgkmcnt(0)
	v_mfma_f32_16x16x32_bf16 v[60:63], v[138:141], v[164:167], v[60:63]
	v_mfma_f32_16x16x32_bf16 v[56:59], v[156:159], v[164:167], v[56:59]
	v_mfma_f32_16x16x32_bf16 v[44:47], v[138:141], v[172:175], v[44:47]
	v_mfma_f32_16x16x32_bf16 v[40:43], v[156:159], v[172:175], v[40:43]
	v_mfma_f32_16x16x32_bf16 v[28:31], v[138:141], v[180:183], v[28:31]
	v_mfma_f32_16x16x32_bf16 v[24:27], v[156:159], v[180:183], v[24:27]
	v_mfma_f32_16x16x32_bf16 v[12:15], v[138:141], v[188:191], v[12:15]
	v_mfma_f32_16x16x32_bf16 v[8:11], v[156:159], v[188:191], v[8:11]
	v_mfma_f32_16x16x32_bf16 v[60:63], v[152:155], v[168:171], v[60:63]
	v_mfma_f32_16x16x32_bf16 v[56:59], v[160:163], v[168:171], v[56:59]
	v_mfma_f32_16x16x32_bf16 v[44:47], v[152:155], v[176:179], v[44:47]
	v_mfma_f32_16x16x32_bf16 v[40:43], v[160:163], v[176:179], v[40:43]
	v_mfma_f32_16x16x32_bf16 v[28:31], v[152:155], v[184:187], v[28:31]
	v_mfma_f32_16x16x32_bf16 v[24:27], v[160:163], v[184:187], v[24:27]
	v_mfma_f32_16x16x32_bf16 v[12:15], v[152:155], v[202:205], v[12:15]
	v_mfma_f32_16x16x32_bf16 v[8:11], v[160:163], v[202:205], v[8:11]
	s_barrier
	s_mov_b32 m0, s89
	s_nop 0
	global_load_lds_dwordx4 v194, s[84:85]
	s_add_i32 m0, s89, 0x2000
	s_nop 0
	global_load_lds_dwordx4 v132, s[84:85]
	s_waitcnt vmcnt(10)
	s_barrier
	v_mfma_f32_16x16x32_bf16 v[52:55], v[206:209], v[164:167], v[52:55]
	v_mfma_f32_16x16x32_bf16 v[48:51], v[214:217], v[164:167], v[48:51]
	v_mfma_f32_16x16x32_bf16 v[36:39], v[206:209], v[172:175], v[36:39]
	v_mfma_f32_16x16x32_bf16 v[32:35], v[214:217], v[172:175], v[32:35]
	v_mfma_f32_16x16x32_bf16 v[20:23], v[206:209], v[180:183], v[20:23]
	v_mfma_f32_16x16x32_bf16 v[16:19], v[214:217], v[180:183], v[16:19]
	v_mfma_f32_16x16x32_bf16 v[4:7], v[206:209], v[188:191], v[4:7]
	v_mfma_f32_16x16x32_bf16 v[0:3], v[214:217], v[188:191], v[0:3]
	v_mfma_f32_16x16x32_bf16 v[52:55], v[210:213], v[168:171], v[52:55]
	v_mfma_f32_16x16x32_bf16 v[48:51], v[218:221], v[168:171], v[48:51]
	v_mfma_f32_16x16x32_bf16 v[36:39], v[210:213], v[176:179], v[36:39]
	v_mfma_f32_16x16x32_bf16 v[32:35], v[218:221], v[176:179], v[32:35]
	v_mfma_f32_16x16x32_bf16 v[20:23], v[210:213], v[184:187], v[20:23]
	v_mfma_f32_16x16x32_bf16 v[16:19], v[218:221], v[184:187], v[16:19]
	v_mfma_f32_16x16x32_bf16 v[4:7], v[210:213], v[202:205], v[4:7]
	v_mfma_f32_16x16x32_bf16 v[0:3], v[218:221], v[202:205], v[0:3]
	s_add_u32 s42, s42, 0x100
	s_addc_u32 s43, s43, 0
	s_add_u32 s16, s16, 0x100
	s_addc_u32 s17, s17, 0
	s_cmp_ge_i32 s44, s34
	s_mov_b32 s18, s44
	s_barrier
	s_cbranch_scc0 .LBB0_165

; #define PG8_STAGE(bufoff, gbase, voff) do { _Pragma("unroll") for (int _i = 0; _i < 2; ++_i) \
;         __builtin_amdgcn_global_load_lds((const unsigned*)((const char*)(gbase) + (voff)[_i]), (LAS unsigned*)(lds + (bufoff) + ldsw + _i * 8192), 16, 0, 0); } while (0)
; #define PG8_LDA(dst, b, h) do { _Pragma("unroll") for (int m = 0; m < 4; ++m) _Pragma("unroll") for (int k = 0; k < 2; ++k) dst[m][k] = *(const LAS bf16x8*)(lds + PG8_SA(b, h) + aoff + m * 2048 + k * 1024); } while (0)
; #define PG8_LDB(dst, b, h) do { _Pragma("unroll") for (int n = 0; n < 2; ++n) _Pragma("unroll") for (int k = 0; k < 2; ++k) dst[n][k] = *(const LAS bf16x8*)(lds + PG8_SB(b, h) + boff + n * 2048 + k * 1024); } while (0)
; #define PG8_MMA(ai, bj, At, Bt) do { __builtin_amdgcn_s_setprio(1); _Pragma("unroll") for (int m = 0; m < 4; ++m) _Pragma("unroll") for (int n = 0; n < 2; ++n) _Pragma("unroll") for (int k = 0; k < 2; ++k) \
;         acc[ai][bj][m][n] = __builtin_amdgcn_mfma_f32_16x16x32_bf16(Bt[n][k], At[m][k], acc[ai][bj][m][n], 0, 0, 0); __builtin_amdgcn_s_setprio(0); } while (0)
; #define PG8_WAIT_V(n) asm volatile("s_waitcnt vmcnt(" #n ")" ::: "memory")
; #define PG8_WAIT_L(n) asm volatile("s_waitcnt lgkmcnt(" #n ")" ::: "memory")
; template <class Epi>
; __device__ __forceinline__ void gemm_phase(LAS unsigned char* lds, const Gemm g, const StaticOrder& S, const Epi& E) {
;     ...
;         for (int t = 0; t < nt; t += 2) {
;             const bool last = (t == nt - 2);
;             const char* a1 = cA + (size_t)(t + 1) * kstep;
;             const char* a2 = last ? nA : cA + (size_t)(t + 2) * kstep; const char* b2 = last ? nB : cB + (size_t)(t + 2) * kstep;
;             const char* a3 = a2 + kstep; const char* b3 = b2 + kstep;
;             PG8_LDB(B0, 0, 0); PG8_SCHED; PG8_LDA(At, 0, 0); PG8_STAGE(PG8_SA(1, 1), a1 + hstep, voffA);
;             PG8_WAIT_L(8); PG8_BAR; PG8_WAIT_L(0); PG8_MMA(0, 0, At, B0); PG8_BAR; PG8_SCHED;
;             PG8_LDB(B1, 0, 1); PG8_STAGE(PG8_SB(0, 0), b2, voffB);
;             PG8_BAR; PG8_WAIT_L(0); PG8_MMA(0, 1, At, B1); PG8_BAR;
;             PG8_LDA(At, 0, 1); PG8_STAGE(PG8_SA(0, 0), a2, voffA);
;             PG8_BAR; PG8_WAIT_L(0); PG8_MMA(1, 0, At, B0); PG8_BAR; PG8_SCHED;
;             PG8_STAGE(PG8_SB(0, 1), b2 + hstep, voffB);
;             PG8_WAIT_V(6); PG8_BAR; PG8_MMA(1, 1, At, B1); PG8_BAR;
.LBB0_528:
	s_add_i32 s42, s18, 2
	s_add_u32 s20, s16, 0x80
	s_addc_u32 s19, s17, 0
	ds_read_b128 v[138:141], v224
	ds_read_b128 v[150:153], v224 offset:1024
	ds_read_b128 v[154:157], v224 offset:2048
	ds_read_b128 v[158:161], v224 offset:3072
	s_cmp_eq_u32 s33, s18
	s_cselect_b32 s18, s10, s20
	s_cselect_b32 s19, s11, s19
	s_cselect_b32 s21, s13, s41
	s_cselect_b32 s20, s12, s40
	s_add_i32 m0, s25, 0xc000
	ds_read_b128 v[162:165], v148
	ds_read_b128 v[166:169], v148 offset:1024
	ds_read_b128 v[170:173], v148 offset:2048
	ds_read_b128 v[174:177], v148 offset:3072
	ds_read_b128 v[178:181], v148 offset:4096
	ds_read_b128 v[182:185], v148 offset:5120
	ds_read_b128 v[186:189], v148 offset:6144
	global_load_lds_dwordx4 v136, s[16:17]
	s_add_i32 m0, s25, 0xe000
	ds_read_b128 v[202:205], v148 offset:7168
	global_load_lds_dwordx4 v134, s[16:17]
	s_waitcnt lgkmcnt(8)
	s_waitcnt vmcnt(10)
	s_barrier
	s_waitcnt lgkmcnt(0)
	v_mfma_f32_16x16x32_bf16 v[124:127], v[138:141], v[162:165], v[124:127]
	v_mfma_f32_16x16x32_bf16 v[120:123], v[154:157], v[162:165], v[120:123]
	v_mfma_f32_16x16x32_bf16 v[108:111], v[138:141], v[170:173], v[108:111]
	v_mfma_f32_16x16x32_bf16 v[104:107], v[154:157], v[170:173], v[104:107]
	v_mfma_f32_16x16x32_bf16 v[92:95], v[138:141], v[178:181], v[92:95]
	v_mfma_f32_16x16x32_bf16 v[88:91], v[154:157], v[178:181], v[88:91]
	v_mfma_f32_16x16x32_bf16 v[76:79], v[138:141], v[186:189], v[76:79]
	v_mfma_f32_16x16x32_bf16 v[72:75], v[154:157], v[186:189], v[72:75]
	v_mfma_f32_16x16x32_bf16 v[124:127], v[150:153], v[166:169], v[124:127]
	v_mfma_f32_16x16x32_bf16 v[120:123], v[158:161], v[166:169], v[120:123]
	v_mfma_f32_16x16x32_bf16 v[108:111], v[150:153], v[174:177], v[108:111]
	v_mfma_f32_16x16x32_bf16 v[104:107], v[158:161], v[174:177], v[104:107]
	v_mfma_f32_16x16x32_bf16 v[92:95], v[150:153], v[182:185], v[92:95]
	v_mfma_f32_16x16x32_bf16 v[88:91], v[158:161], v[182:185], v[88:91]
	v_mfma_f32_16x16x32_bf16 v[76:79], v[150:153], v[202:205], v[76:79]
	v_mfma_f32_16x16x32_bf16 v[72:75], v[158:161], v[202:205], v[72:75]
	s_barrier
	s_add_u32 s80, s20, 0x80
	s_addc_u32 s81, s21, 0
	s_mov_b32 m0, s86
	ds_read_b128 v[206:209], v225
	ds_read_b128 v[210:213], v225 offset:1024
	ds_read_b128 v[214:217], v225 offset:2048
	global_load_lds_dwordx4 v194, s[20:21]
	s_add_i32 m0, s86, 0x2000
	ds_read_b128 v[218:221], v225 offset:3072
	global_load_lds_dwordx4 v132, s[20:21]
	s_waitcnt vmcnt(10)
	s_barrier
	s_waitcnt lgkmcnt(0)
	v_mfma_f32_16x16x32_bf16 v[116:119], v[206:209], v[162:165], v[116:119]
	v_mfma_f32_16x16x32_bf16 v[112:115], v[214:217], v[162:165], v[112:115]
	v_mfma_f32_16x16x32_bf16 v[100:103], v[206:209], v[170:173], v[100:103]
	v_mfma_f32_16x16x32_bf16 v[96:99], v[214:217], v[170:173], v[96:99]
	v_mfma_f32_16x16x32_bf16 v[84:87], v[206:209], v[178:181], v[84:87]
	v_mfma_f32_16x16x32_bf16 v[80:83], v[214:217], v[178:181], v[80:83]
	v_mfma_f32_16x16x32_bf16 v[68:71], v[206:209], v[186:189], v[68:71]
	v_mfma_f32_16x16x32_bf16 v[64:67], v[214:217], v[186:189], v[64:67]
	v_mfma_f32_16x16x32_bf16 v[116:119], v[210:213], v[166:169], v[116:119]
	v_mfma_f32_16x16x32_bf16 v[112:115], v[218:221], v[166:169], v[112:115]
	v_mfma_f32_16x16x32_bf16 v[100:103], v[210:213], v[174:177], v[100:103]
	v_mfma_f32_16x16x32_bf16 v[96:99], v[218:221], v[174:177], v[96:99]
	v_mfma_f32_16x16x32_bf16 v[84:87], v[210:213], v[182:185], v[84:87]
	v_mfma_f32_16x16x32_bf16 v[80:83], v[218:221], v[182:185], v[80:83]
	v_mfma_f32_16x16x32_bf16 v[68:71], v[210:213], v[202:205], v[68:71]
	v_mfma_f32_16x16x32_bf16 v[64:67], v[218:221], v[202:205], v[64:67]
	s_mov_b32 m0, s25
	s_add_u32 s82, s18, 0x80
	s_addc_u32 s83, s19, 0
	s_barrier
	ds_read_b128 v[162:165], v148 offset:16384
	ds_read_b128 v[166:169], v148 offset:17408
	ds_read_b128 v[170:173], v148 offset:18432
	ds_read_b128 v[174:177], v148 offset:19456
	ds_read_b128 v[178:181], v148 offset:20480
	ds_read_b128 v[182:185], v148 offset:21504
	ds_read_b128 v[186:189], v148 offset:22528
	global_load_lds_dwordx4 v128, s[18:19]
	s_mov_b32 m0, s26
	ds_read_b128 v[202:205], v148 offset:23552
	global_load_lds_dwordx4 v130, s[18:19]
	s_barrier
	s_waitcnt lgkmcnt(0)
	v_mfma_f32_16x16x32_bf16 v[60:63], v[138:141], v[162:165], v[60:63]
	v_mfma_f32_16x16x32_bf16 v[56:59], v[154:157], v[162:165], v[56:59]
	v_mfma_f32_16x16x32_bf16 v[44:47], v[138:141], v[170:173], v[44:47]
	v_mfma_f32_16x16x32_bf16 v[40:43], v[154:157], v[170:173], v[40:43]
	v_mfma_f32_16x16x32_bf16 v[28:31], v[138:141], v[178:181], v[28:31]
	v_mfma_f32_16x16x32_bf16 v[24:27], v[154:157], v[178:181], v[24:27]
	v_mfma_f32_16x16x32_bf16 v[12:15], v[138:141], v[186:189], v[12:15]
	v_mfma_f32_16x16x32_bf16 v[8:11], v[154:157], v[186:189], v[8:11]
	v_mfma_f32_16x16x32_bf16 v[60:63], v[150:153], v[166:169], v[60:63]
	v_mfma_f32_16x16x32_bf16 v[56:59], v[158:161], v[166:169], v[56:59]
	v_mfma_f32_16x16x32_bf16 v[44:47], v[150:153], v[174:177], v[44:47]
	v_mfma_f32_16x16x32_bf16 v[40:43], v[158:161], v[174:177], v[40:43]
	v_mfma_f32_16x16x32_bf16 v[28:31], v[150:153], v[182:185], v[28:31]
	v_mfma_f32_16x16x32_bf16 v[24:27], v[158:161], v[182:185], v[24:27]
	v_mfma_f32_16x16x32_bf16 v[12:15], v[150:153], v[202:205], v[12:15]
	v_mfma_f32_16x16x32_bf16 v[8:11], v[158:161], v[202:205], v[8:11]
	s_barrier
	s_add_u32 s20, s20, s2
	s_addc_u32 s21, s21, s3
	s_add_u32 s84, s20, 0x80
	s_mov_b32 m0, s87
	s_addc_u32 s85, s21, 0
	global_load_lds_dwordx4 v194, s[20:21]
	s_add_i32 m0, s87, 0x2000
	s_nop 0
	global_load_lds_dwordx4 v132, s[20:21]
	s_waitcnt vmcnt(10)
	s_barrier
; #define PG8_STAGE(bufoff, gbase, voff) do { _Pragma("unroll") for (int _i = 0; _i < 2; ++_i) \
;         __builtin_amdgcn_global_load_lds((const unsigned*)((const char*)(gbase) + (voff)[_i]), (LAS unsigned*)(lds + (bufoff) + ldsw + _i * 8192), 16, 0, 0); } while (0)
; #define PG8_LDA(dst, b, h) do { _Pragma("unroll") for (int m = 0; m < 4; ++m) _Pragma("unroll") for (int k = 0; k < 2; ++k) dst[m][k] = *(const LAS bf16x8*)(lds + PG8_SA(b, h) + aoff + m * 2048 + k * 1024); } while (0)
; #define PG8_LDB(dst, b, h) do { _Pragma("unroll") for (int n = 0; n < 2; ++n) _Pragma("unroll") for (int k = 0; k < 2; ++k) dst[n][k] = *(const LAS bf16x8*)(lds + PG8_SB(b, h) + boff + n * 2048 + k * 1024); } while (0)
; #define PG8_MMA(ai, bj, At, Bt) do { __builtin_amdgcn_s_setprio(1); _Pragma("unroll") for (int m = 0; m < 4; ++m) _Pragma("unroll") for (int n = 0; n < 2; ++n) _Pragma("unroll") for (int k = 0; k < 2; ++k) \
;         acc[ai][bj][m][n] = __builtin_amdgcn_mfma_f32_16x16x32_bf16(Bt[n][k], At[m][k], acc[ai][bj][m][n], 0, 0, 0); __builtin_amdgcn_s_setprio(0); } while (0)
; #define PG8_WAIT_V(n) asm volatile("s_waitcnt vmcnt(" #n ")" ::: "memory")
; #define PG8_WAIT_L(n) asm volatile("s_waitcnt lgkmcnt(" #n ")" ::: "memory")
; #define PG8_BAR __builtin_amdgcn_s_barrier()
; #define PG8_SCHED __builtin_amdgcn_sched_barrier(0)
; template <class Epi>
; __device__ __forceinline__ void gemm_phase(LAS unsigned char* lds, const Gemm g, const StaticOrder& S, const Epi& E) {
;     ...
;             PG8_WAIT_V(6); PG8_BAR; PG8_MMA(1, 1, At, B1); PG8_BAR;
;             PG8_LDB(B0, 1, 0); PG8_SCHED; PG8_LDA(At, 1, 0); PG8_STAGE(PG8_SA(0, 1), a2 + hstep, voffA);
;             PG8_WAIT_L(8); PG8_BAR; PG8_WAIT_L(0); PG8_MMA(0, 0, At, B0); PG8_BAR; PG8_SCHED;
;             PG8_LDB(B1, 1, 1); PG8_STAGE(PG8_SB(1, 0), b3, voffB);
;             PG8_BAR; PG8_WAIT_L(0); PG8_MMA(0, 1, At, B1); PG8_BAR;
	v_mfma_f32_16x16x32_bf16 v[52:55], v[206:209], v[162:165], v[52:55]
	v_mfma_f32_16x16x32_bf16 v[48:51], v[214:217], v[162:165], v[48:51]
	v_mfma_f32_16x16x32_bf16 v[36:39], v[206:209], v[170:173], v[36:39]
	v_mfma_f32_16x16x32_bf16 v[32:35], v[214:217], v[170:173], v[32:35]
	v_mfma_f32_16x16x32_bf16 v[20:23], v[206:209], v[178:181], v[20:23]
	v_mfma_f32_16x16x32_bf16 v[16:19], v[214:217], v[178:181], v[16:19]
	v_mfma_f32_16x16x32_bf16 v[4:7], v[206:209], v[186:189], v[4:7]
	v_mfma_f32_16x16x32_bf16 v[0:3], v[214:217], v[186:189], v[0:3]
	v_mfma_f32_16x16x32_bf16 v[52:55], v[210:213], v[166:169], v[52:55]
	v_mfma_f32_16x16x32_bf16 v[48:51], v[218:221], v[166:169], v[48:51]
	v_mfma_f32_16x16x32_bf16 v[36:39], v[210:213], v[174:177], v[36:39]
	v_mfma_f32_16x16x32_bf16 v[32:35], v[218:221], v[174:177], v[32:35]
	v_mfma_f32_16x16x32_bf16 v[20:23], v[210:213], v[182:185], v[20:23]
	v_mfma_f32_16x16x32_bf16 v[16:19], v[218:221], v[182:185], v[16:19]
	v_mfma_f32_16x16x32_bf16 v[4:7], v[210:213], v[202:205], v[4:7]
	v_mfma_f32_16x16x32_bf16 v[0:3], v[218:221], v[202:205], v[0:3]
	s_barrier
	ds_read_b128 v[138:141], v226
	ds_read_b128 v[150:153], v226 offset:1024
	ds_read_b128 v[154:157], v226 offset:2048
	ds_read_b128 v[158:161], v226 offset:3072
	s_add_u32 s18, s18, s2
	s_addc_u32 s19, s19, s3
	s_mov_b32 m0, s27
	ds_read_b128 v[162:165], v148 offset:32768
	ds_read_b128 v[166:169], v148 offset:33792
	ds_read_b128 v[170:173], v148 offset:34816
	ds_read_b128 v[174:177], v148 offset:35840
	ds_read_b128 v[178:181], v148 offset:36864
	ds_read_b128 v[182:185], v148 offset:37888
	ds_read_b128 v[186:189], v148 offset:38912
	global_load_lds_dwordx4 v128, s[18:19]
	s_mov_b32 m0, s28
	ds_read_b128 v[202:205], v148 offset:39936
	global_load_lds_dwordx4 v130, s[18:19]
	s_waitcnt lgkmcnt(8)
	s_waitcnt vmcnt(10)
	s_barrier
	s_waitcnt lgkmcnt(0)
	v_mfma_f32_16x16x32_bf16 v[124:127], v[138:141], v[162:165], v[124:127]
	v_mfma_f32_16x16x32_bf16 v[120:123], v[154:157], v[162:165], v[120:123]
	v_mfma_f32_16x16x32_bf16 v[108:111], v[138:141], v[170:173], v[108:111]
	v_mfma_f32_16x16x32_bf16 v[104:107], v[154:157], v[170:173], v[104:107]
	v_mfma_f32_16x16x32_bf16 v[92:95], v[138:141], v[178:181], v[92:95]
	v_mfma_f32_16x16x32_bf16 v[88:91], v[154:157], v[178:181], v[88:91]
	v_mfma_f32_16x16x32_bf16 v[76:79], v[138:141], v[186:189], v[76:79]
	v_mfma_f32_16x16x32_bf16 v[72:75], v[154:157], v[186:189], v[72:75]
	v_mfma_f32_16x16x32_bf16 v[124:127], v[150:153], v[166:169], v[124:127]
	v_mfma_f32_16x16x32_bf16 v[120:123], v[158:161], v[166:169], v[120:123]
	v_mfma_f32_16x16x32_bf16 v[108:111], v[150:153], v[174:177], v[108:111]
	v_mfma_f32_16x16x32_bf16 v[104:107], v[158:161], v[174:177], v[104:107]
	v_mfma_f32_16x16x32_bf16 v[92:95], v[150:153], v[182:185], v[92:95]
	v_mfma_f32_16x16x32_bf16 v[88:91], v[158:161], v[182:185], v[88:91]
	v_mfma_f32_16x16x32_bf16 v[76:79], v[150:153], v[202:205], v[76:79]
	v_mfma_f32_16x16x32_bf16 v[72:75], v[158:161], v[202:205], v[72:75]
	s_barrier
	s_mov_b32 m0, s88
	ds_read_b128 v[206:209], v227
	ds_read_b128 v[210:213], v227 offset:1024
	ds_read_b128 v[214:217], v227 offset:2048
	global_load_lds_dwordx4 v194, s[80:81]
	s_add_i32 m0, s88, 0x2000
	ds_read_b128 v[218:221], v227 offset:3072
	global_load_lds_dwordx4 v132, s[80:81]
	s_waitcnt vmcnt(10)
	s_barrier
; #define PG8_STAGE(bufoff, gbase, voff) do { _Pragma("unroll") for (int _i = 0; _i < 2; ++_i) \
;         __builtin_amdgcn_global_load_lds((const unsigned*)((const char*)(gbase) + (voff)[_i]), (LAS unsigned*)(lds + (bufoff) + ldsw + _i * 8192), 16, 0, 0); } while (0)
; #define PG8_LDA(dst, b, h) do { _Pragma("unroll") for (int m = 0; m < 4; ++m) _Pragma("unroll") for (int k = 0; k < 2; ++k) dst[m][k] = *(const LAS bf16x8*)(lds + PG8_SA(b, h) + aoff + m * 2048 + k * 1024); } while (0)
; #define PG8_MMA(ai, bj, At, Bt) do { __builtin_amdgcn_s_setprio(1); _Pragma("unroll") for (int m = 0; m < 4; ++m) _Pragma("unroll") for (int n = 0; n < 2; ++n) _Pragma("unroll") for (int k = 0; k < 2; ++k) \
;         acc[ai][bj][m][n] = __builtin_amdgcn_mfma_f32_16x16x32_bf16(Bt[n][k], At[m][k], acc[ai][bj][m][n], 0, 0, 0); __builtin_amdgcn_s_setprio(0); } while (0)
; #define PG8_WAIT_V(n) asm volatile("s_waitcnt vmcnt(" #n ")" ::: "memory")
; #define PG8_WAIT_L(n) asm volatile("s_waitcnt lgkmcnt(" #n ")" ::: "memory")
; #define PG8_BAR __builtin_amdgcn_s_barrier()
; #define PG8_SCHED __builtin_amdgcn_sched_barrier(0)
; template <class Epi>
; __device__ __forceinline__ void gemm_phase(LAS unsigned char* lds, const Gemm g, const StaticOrder& S, const Epi& E) {
;     ...
;             PG8_BAR; PG8_WAIT_L(0); PG8_MMA(0, 1, At, B1); PG8_BAR;
;             PG8_LDA(At, 1, 1); PG8_STAGE(PG8_SA(1, 0), a3, voffA);
;             PG8_BAR; PG8_WAIT_L(0); PG8_MMA(1, 0, At, B0); PG8_BAR; PG8_SCHED;
;             PG8_STAGE(PG8_SB(1, 1), b3 + hstep, voffB);
;             PG8_WAIT_V(6); PG8_BAR; PG8_MMA(1, 1, At, B1); PG8_BAR;
	s_waitcnt lgkmcnt(0)
	v_mfma_f32_16x16x32_bf16 v[116:119], v[206:209], v[162:165], v[116:119]
	v_mfma_f32_16x16x32_bf16 v[112:115], v[214:217], v[162:165], v[112:115]
	v_mfma_f32_16x16x32_bf16 v[100:103], v[206:209], v[170:173], v[100:103]
	v_mfma_f32_16x16x32_bf16 v[96:99], v[214:217], v[170:173], v[96:99]
	v_mfma_f32_16x16x32_bf16 v[84:87], v[206:209], v[178:181], v[84:87]
	v_mfma_f32_16x16x32_bf16 v[80:83], v[214:217], v[178:181], v[80:83]
	v_mfma_f32_16x16x32_bf16 v[68:71], v[206:209], v[186:189], v[68:71]
	v_mfma_f32_16x16x32_bf16 v[64:67], v[214:217], v[186:189], v[64:67]
	v_mfma_f32_16x16x32_bf16 v[116:119], v[210:213], v[166:169], v[116:119]
	v_mfma_f32_16x16x32_bf16 v[112:115], v[218:221], v[166:169], v[112:115]
	v_mfma_f32_16x16x32_bf16 v[100:103], v[210:213], v[174:177], v[100:103]
	v_mfma_f32_16x16x32_bf16 v[96:99], v[218:221], v[174:177], v[96:99]
	v_mfma_f32_16x16x32_bf16 v[84:87], v[210:213], v[182:185], v[84:87]
	v_mfma_f32_16x16x32_bf16 v[80:83], v[218:221], v[182:185], v[80:83]
	v_mfma_f32_16x16x32_bf16 v[68:71], v[210:213], v[202:205], v[68:71]
	v_mfma_f32_16x16x32_bf16 v[64:67], v[218:221], v[202:205], v[64:67]
	s_mov_b32 m0, s29
	s_barrier
	ds_read_b128 v[162:165], v148 offset:49152
	ds_read_b128 v[166:169], v148 offset:50176
	ds_read_b128 v[170:173], v148 offset:51200
	ds_read_b128 v[174:177], v148 offset:52224
	ds_read_b128 v[178:181], v148 offset:53248
	ds_read_b128 v[182:185], v148 offset:54272
	ds_read_b128 v[186:189], v148 offset:55296
	global_load_lds_dwordx4 v128, s[82:83]
	s_mov_b32 m0, s30
	ds_read_b128 v[202:205], v148 offset:56320
	global_load_lds_dwordx4 v130, s[82:83]
	s_barrier
	s_waitcnt lgkmcnt(0)
	v_mfma_f32_16x16x32_bf16 v[60:63], v[138:141], v[162:165], v[60:63]
	v_mfma_f32_16x16x32_bf16 v[56:59], v[154:157], v[162:165], v[56:59]
	v_mfma_f32_16x16x32_bf16 v[44:47], v[138:141], v[170:173], v[44:47]
	v_mfma_f32_16x16x32_bf16 v[40:43], v[154:157], v[170:173], v[40:43]
	v_mfma_f32_16x16x32_bf16 v[28:31], v[138:141], v[178:181], v[28:31]
	v_mfma_f32_16x16x32_bf16 v[24:27], v[154:157], v[178:181], v[24:27]
	v_mfma_f32_16x16x32_bf16 v[12:15], v[138:141], v[186:189], v[12:15]
	v_mfma_f32_16x16x32_bf16 v[8:11], v[154:157], v[186:189], v[8:11]
	v_mfma_f32_16x16x32_bf16 v[60:63], v[150:153], v[166:169], v[60:63]
	v_mfma_f32_16x16x32_bf16 v[56:59], v[158:161], v[166:169], v[56:59]
	v_mfma_f32_16x16x32_bf16 v[44:47], v[150:153], v[174:177], v[44:47]
	v_mfma_f32_16x16x32_bf16 v[40:43], v[158:161], v[174:177], v[40:43]
	v_mfma_f32_16x16x32_bf16 v[28:31], v[150:153], v[182:185], v[28:31]
	v_mfma_f32_16x16x32_bf16 v[24:27], v[158:161], v[182:185], v[24:27]
	v_mfma_f32_16x16x32_bf16 v[12:15], v[150:153], v[202:205], v[12:15]
	v_mfma_f32_16x16x32_bf16 v[8:11], v[158:161], v[202:205], v[8:11]
	s_barrier
	s_mov_b32 m0, s89
	s_nop 0
	global_load_lds_dwordx4 v194, s[84:85]
	s_add_i32 m0, s89, 0x2000
	s_nop 0
	global_load_lds_dwordx4 v132, s[84:85]
	s_waitcnt vmcnt(10)
	s_barrier
	v_mfma_f32_16x16x32_bf16 v[52:55], v[206:209], v[162:165], v[52:55]
	v_mfma_f32_16x16x32_bf16 v[48:51], v[214:217], v[162:165], v[48:51]
	v_mfma_f32_16x16x32_bf16 v[36:39], v[206:209], v[170:173], v[36:39]
	v_mfma_f32_16x16x32_bf16 v[32:35], v[214:217], v[170:173], v[32:35]
	v_mfma_f32_16x16x32_bf16 v[20:23], v[206:209], v[178:181], v[20:23]
	v_mfma_f32_16x16x32_bf16 v[16:19], v[214:217], v[178:181], v[16:19]
	v_mfma_f32_16x16x32_bf16 v[4:7], v[206:209], v[186:189], v[4:7]
	v_mfma_f32_16x16x32_bf16 v[0:3], v[214:217], v[186:189], v[0:3]
	v_mfma_f32_16x16x32_bf16 v[52:55], v[210:213], v[166:169], v[52:55]
	v_mfma_f32_16x16x32_bf16 v[48:51], v[218:221], v[166:169], v[48:51]
	v_mfma_f32_16x16x32_bf16 v[36:39], v[210:213], v[174:177], v[36:39]
	v_mfma_f32_16x16x32_bf16 v[32:35], v[218:221], v[174:177], v[32:35]
	v_mfma_f32_16x16x32_bf16 v[20:23], v[210:213], v[182:185], v[20:23]
	v_mfma_f32_16x16x32_bf16 v[16:19], v[218:221], v[182:185], v[16:19]
	v_mfma_f32_16x16x32_bf16 v[4:7], v[210:213], v[202:205], v[4:7]
	v_mfma_f32_16x16x32_bf16 v[0:3], v[218:221], v[202:205], v[0:3]
	s_add_u32 s40, s40, 0x100
	s_addc_u32 s41, s41, 0
	s_add_u32 s16, s16, 0x100
	s_addc_u32 s17, s17, 0
	s_cmp_ge_i32 s42, s31
	s_mov_b32 s18, s42
	s_barrier
	s_cbranch_scc0 .LBB0_528
